# P0 tile loop: next tile's descriptor selection moved ahead of the tile barrier (DMA issues right after the barrier)
# speedup vs baseline: 1.0045x; 1.0015x over previous
.LBB0_81:
	s_add_i32 s0, s70, 1
	s_cmp_ge_i32 s0, s10
	s_cselect_b32 s101, 1, 0
	s_cbranch_scc1 .Lp0_desc_done
	s_cmpk_gt_i32 s70, 0x1fe
	s_cbranch_scc0 .LBB0_88
	s_cmpk_gt_u32 s0, 0x23f
	s_cbranch_scc0 .LBB0_89
	s_cmpk_gt_u32 s0, 0x27f
	s_cbranch_scc0 .LBB0_90
	s_cmpk_gt_u32 s0, 0x2bf
	s_cbranch_scc0 .LBB0_92
	s_add_i32 s73, s9, 64
	s_cmpk_gt_u32 s0, 0x3bf
	s_cbranch_scc0 .LBB0_93
	v_readlane_b32 s16, v251, 2
	s_add_i32 s0, s76, 4
	v_readlane_b32 s28, v251, 14
	v_readlane_b32 s29, v251, 15
	s_and_b32 s72, s0, 0x7fffff00
	s_and_b32 s88, s73, 0xfc0
	v_readlane_b32 s17, v251, 3
	v_readlane_b32 s18, v251, 4
	v_readlane_b32 s19, v251, 5
	v_readlane_b32 s20, v251, 6
	v_readlane_b32 s21, v251, 7
	v_readlane_b32 s22, v251, 8
	v_readlane_b32 s23, v251, 9
	v_readlane_b32 s24, v251, 10
	v_readlane_b32 s25, v251, 11
	v_readlane_b32 s26, v251, 12
	v_readlane_b32 s27, v251, 13
	v_readlane_b32 s30, v251, 16
	v_readlane_b32 s31, v251, 17
	s_mov_b64 s[0:1], s[28:29]
	s_mov_b64 s[70:71], 0x400
	s_cbranch_execz .LBB0_94
	s_branch .LBB0_95

.LBB0_103:
.Lp0_desc_done:
	s_waitcnt vmcnt(0) lgkmcnt(0)
	s_barrier
	s_cmp_lg_u32 s101, 0
	s_cbranch_scc1 .LBB0_104
	s_bitcmp1_b32 s65, 0
	s_cselect_b32 s73, 0, 0x10400
	s_add_i32 s89, s73, 0
	s_add_i32 s73, s88, s11
	s_mul_i32 s74, s71, s73
	s_mul_hi_u32 s75, s70, s73
	s_add_i32 s75, s75, s74
	s_mul_i32 s74, s70, s73
	s_lshl_b64 s[74:75], s[74:75], 2
	s_add_u32 s74, s0, s74
	s_addc_u32 s75, s1, s75
	s_ashr_i32 s73, s72, 31
	s_lshl_b64 s[72:73], s[72:73], 2
	s_add_u32 s74, s74, s72
	s_addc_u32 s75, s75, s73
	v_lshl_add_u64 v[20:21], s[74:75], 0, v[0:1]
	s_add_i32 s74, s88, s33
	s_mul_i32 s75, s71, s74
	s_mul_hi_u32 s90, s70, s74
	s_add_i32 s75, s90, s75
	s_mul_i32 s74, s70, s74
	s_add_i32 m0, s89, s3
	s_lshl_b64 s[74:75], s[74:75], 2
	s_add_u32 s74, s0, s74
	s_addc_u32 s75, s1, s75
	s_add_u32 s74, s74, s72
	s_addc_u32 s75, s75, s73
	global_load_lds_dwordx4 v[20:21], off nt
	v_lshl_add_u64 v[20:21], s[74:75], 0, v[0:1]
	s_add_i32 s74, s88, s35
	s_mul_i32 s75, s71, s74
	s_mul_hi_u32 s90, s70, s74
	s_add_i32 s75, s90, s75
	s_mul_i32 s74, s70, s74
	s_add_i32 s89, s89, s34
	s_lshl_b64 s[74:75], s[74:75], 2
	s_add_u32 s74, s0, s74
	s_addc_u32 s75, s1, s75
	s_add_u32 s74, s74, s72
	s_mov_b32 m0, s89
	s_addc_u32 s75, s75, s73
	global_load_lds_dwordx4 v[20:21], off nt
	v_lshl_add_u64 v[20:21], s[74:75], 0, v[0:1]
	s_add_i32 s74, s88, s56
	s_mul_i32 s75, s71, s74
	s_mul_hi_u32 s90, s70, s74
	s_add_i32 s75, s90, s75
	s_mul_i32 s74, s70, s74
	s_add_i32 m0, s89, 0x410
	s_lshl_b64 s[74:75], s[74:75], 2
	s_add_u32 s74, s0, s74
	s_addc_u32 s75, s1, s75
	s_add_u32 s74, s74, s72
	s_addc_u32 s75, s75, s73
	global_load_lds_dwordx4 v[20:21], off nt
	v_lshl_add_u64 v[20:21], s[74:75], 0, v[0:1]
	s_add_i32 s74, s88, s57
	s_mul_i32 s75, s71, s74
	s_mul_hi_u32 s90, s70, s74
	s_add_i32 s75, s90, s75
	s_mul_i32 s74, s70, s74
	s_add_i32 m0, s89, 0x820
	s_lshl_b64 s[74:75], s[74:75], 2
	s_add_u32 s74, s0, s74
	s_addc_u32 s75, s1, s75
	s_add_u32 s74, s74, s72
	s_addc_u32 s75, s75, s73
	global_load_lds_dwordx4 v[20:21], off nt
	v_lshl_add_u64 v[20:21], s[74:75], 0, v[0:1]
	s_add_i32 s74, s88, s59
	s_mul_i32 s75, s71, s74
	s_mul_hi_u32 s90, s70, s74
	s_add_i32 s75, s90, s75
	s_mul_i32 s74, s70, s74
	s_add_i32 m0, s89, 0xc30
	s_lshl_b64 s[74:75], s[74:75], 2
	s_add_u32 s74, s0, s74
	s_addc_u32 s75, s1, s75
	s_add_u32 s74, s74, s72
	s_addc_u32 s75, s75, s73
	global_load_lds_dwordx4 v[20:21], off nt
	v_lshl_add_u64 v[20:21], s[74:75], 0, v[0:1]
	s_add_i32 s74, s88, s61
	s_mul_i32 s75, s71, s74
	s_mul_hi_u32 s90, s70, s74
	s_add_i32 s75, s90, s75
	s_mul_i32 s74, s70, s74
	s_add_i32 m0, s89, 0x1040
	s_lshl_b64 s[74:75], s[74:75], 2
	s_add_u32 s74, s0, s74
	s_addc_u32 s75, s1, s75
	s_add_u32 s74, s74, s72
	s_addc_u32 s75, s75, s73
	global_load_lds_dwordx4 v[20:21], off nt
	v_lshl_add_u64 v[20:21], s[74:75], 0, v[0:1]
	s_add_i32 s74, s88, s64
	s_mul_i32 s71, s71, s74
	s_mul_hi_u32 s75, s70, s74
	s_add_i32 s71, s75, s71
	s_mul_i32 s70, s70, s74
	s_add_i32 m0, s89, 0x1450
	s_lshl_b64 s[70:71], s[70:71], 2
	s_add_u32 s0, s0, s70
	s_addc_u32 s1, s1, s71
	s_add_u32 s0, s0, s72
	s_addc_u32 s1, s1, s73
	global_load_lds_dwordx4 v[20:21], off nt
	v_lshl_add_u64 v[20:21], s[0:1], 0, v[0:1]
	s_add_i32 m0, s89, 0x1860
	s_nop 0
	global_load_lds_dwordx4 v[20:21], off nt
